# rope phase: the eight lane-constant rope frequencies of the differential q/k loop computed once before the row loop instead of per pass (40 fewer instructions, 8 fewer transcendentals per pass)
# baseline (speedup 1.0000x reference)
.Lgb3_done:
.LBB0_989:
	s_or_b64 exec, exec, s[2:3]
	v_mov_b32_e32 v0, v214
	v_readlane_b32 s3, v253, 0
	s_waitcnt lgkmcnt(0)
	s_barrier
	s_lshl_b32 s3, s3, 3
	v_readfirstlane_b32 s2, v0
	s_ashr_i32 s2, s2, 6
	s_add_i32 s2, s3, s2
	s_cmpk_gt_i32 s2, 0x23ff
	s_cbranch_scc1 .LBB0_1012
	v_and_b32_e32 v58, 63, v0
	v_lshlrev_b32_e32 v3, 3, v0
	v_bfe_u32 v1, v0, 2, 1
	v_and_b32_e32 v6, 24, v3
	v_mov_b32_e32 v3, s71
	v_mov_b32_e32 v5, s69
	v_cmp_gt_u32_e32 vcc, 48, v58
	v_lshlrev_b32_e32 v4, 6, v1
	v_lshlrev_b32_e32 v176, 8, v1
	v_cndmask_b32_e32 v9, v3, v5, vcc
	v_mov_b32_e32 v3, s70
	v_mov_b32_e32 v5, s68
	v_cmp_eq_u32_e64 s[6:7], 0, v1
	v_xor_b32_e32 v1, 1, v218
	v_cndmask_b32_e32 v8, v3, v5, vcc
	v_cmp_lt_i32_e32 vcc, v1, v219
	v_or_b32_e32 v3, 1, v6
	v_or_b32_e32 v5, 2, v6
	v_cndmask_b32_e32 v1, v218, v1, vcc
	v_lshlrev_b32_e32 v59, 2, v1
	v_xor_b32_e32 v1, 2, v218
	v_cmp_lt_i32_e32 vcc, v1, v219
	v_or_b32_e32 v7, 3, v6
	v_cvt_f32_ubyte0_e32 v3, v3
	v_cndmask_b32_e32 v1, v218, v1, vcc
	v_lshlrev_b32_e32 v60, 2, v1
	v_xor_b32_e32 v1, 4, v218
	v_cmp_lt_i32_e32 vcc, v1, v219
	v_cvt_f32_ubyte0_e32 v5, v5
	v_cvt_f32_ubyte0_e32 v7, v7
	v_cndmask_b32_e32 v1, v218, v1, vcc
	v_lshlrev_b32_e32 v61, 2, v1
	v_cvt_f32_ubyte0_e32 v1, v6
	v_mul_f32_e32 v1, 0xbed49a78, v1
	v_exp_f32_e32 v1, v1
	v_mul_f32_e32 v3, 0xbed49a78, v3
	v_mul_f32_e32 v5, 0xbed49a78, v5
	v_mul_f32_e32 v7, 0xbed49a78, v7
	v_exp_f32_e32 v3, v3
	v_exp_f32_e32 v5, v5
	v_exp_f32_e32 v7, v7
	v_mul_f32_e32 v62, 0.15915494, v1
	v_or_b32_e32 v1, 4, v6
	v_cvt_f32_ubyte0_e32 v1, v1
	v_mul_f32_e32 v1, 0xbed49a78, v1
	v_mul_f32_e32 v63, 0.15915494, v3
	v_mul_f32_e32 v64, 0.15915494, v5
	v_mul_f32_e32 v65, 0.15915494, v7
	v_exp_f32_e32 v1, v1
	v_or_b32_e32 v3, 5, v6
	v_or_b32_e32 v5, 6, v6
	v_or_b32_e32 v7, 7, v6
	v_cvt_f32_ubyte0_e32 v3, v3
	v_cvt_f32_ubyte0_e32 v5, v5
	v_cvt_f32_ubyte0_e32 v7, v7
	v_mul_f32_e32 v3, 0xbed49a78, v3
	v_mul_f32_e32 v5, 0xbed49a78, v5
	v_mul_f32_e32 v7, 0xbed49a78, v7
	s_lshl_b32 s90, s96, 7
	v_exp_f32_e32 v3, v3
	v_exp_f32_e32 v5, v5
	v_exp_f32_e32 v7, v7
	v_lshlrev_b32_e32 v2, 4, v0
	v_lshl_add_u64 v[8:9], s[90:91], 2, v[8:9]
	v_mul_f32_e32 v66, 0.15915494, v1
	v_lshlrev_b32_e32 v1, 5, v0
	v_and_b32_e32 v0, 1, v0
	v_lshl_add_u64 v[8:9], v[8:9], 0, v[176:177]
	v_lshlrev_b32_e32 v176, 2, v6
	v_lshlrev_b32_e32 v0, 4, v0
	s_movk_i32 s3, 0x7c0
	v_readlane_b32 s4, v253, 56
	v_and_b32_e32 v2, 0x380, v2
	v_lshl_add_u64 v[8:9], v[8:9], 0, v[176:177]
	v_and_or_b32 v176, v1, s3, v0
	v_readlane_b32 s5, v253, 57
	v_mul_f32_e32 v67, 0.15915494, v3
	v_mul_f32_e32 v68, 0.15915494, v5
	v_mul_f32_e32 v69, 0.15915494, v7
	v_lshlrev_b32_e32 v70, 3, v58
	v_and_b32_e32 v158, 8, v70
	v_or_b32_e32 v150, 0, v158
	v_cvt_f32_ubyte0_e32 v150, v150
	v_mul_f32_e32 v150, 0xbf549a78, v150
	v_exp_f32_e32 v150, v150
	s_nop 0
	v_mul_f32_e32 v150, 0.15915494, v150
	v_or_b32_e32 v151, 1, v158
	v_cvt_f32_ubyte0_e32 v151, v151
	v_mul_f32_e32 v151, 0xbf549a78, v151
	v_exp_f32_e32 v151, v151
	s_nop 0
	v_mul_f32_e32 v151, 0.15915494, v151
	v_or_b32_e32 v152, 2, v158
	v_cvt_f32_ubyte0_e32 v152, v152
	v_mul_f32_e32 v152, 0xbf549a78, v152
	v_exp_f32_e32 v152, v152
	s_nop 0
	v_mul_f32_e32 v152, 0.15915494, v152
	v_or_b32_e32 v153, 3, v158
	v_cvt_f32_ubyte0_e32 v153, v153
	v_mul_f32_e32 v153, 0xbf549a78, v153
	v_exp_f32_e32 v153, v153
	s_nop 0
	v_mul_f32_e32 v153, 0.15915494, v153
	v_or_b32_e32 v154, 4, v158
	v_cvt_f32_ubyte0_e32 v154, v154
	v_mul_f32_e32 v154, 0xbf549a78, v154
	v_exp_f32_e32 v154, v154
	s_nop 0
	v_mul_f32_e32 v154, 0.15915494, v154
	v_or_b32_e32 v155, 5, v158
	v_cvt_f32_ubyte0_e32 v155, v155
	v_mul_f32_e32 v155, 0xbf549a78, v155
	v_exp_f32_e32 v155, v155
	s_nop 0
	v_mul_f32_e32 v155, 0.15915494, v155
	v_or_b32_e32 v156, 6, v158
	v_cvt_f32_ubyte0_e32 v156, v156
	v_mul_f32_e32 v156, 0xbf549a78, v156
	v_exp_f32_e32 v156, v156
	s_nop 0
	v_mul_f32_e32 v156, 0.15915494, v156
	v_or_b32_e32 v157, 7, v158
	v_cvt_f32_ubyte0_e32 v157, v157
	v_mul_f32_e32 v157, 0xbf549a78, v157
	v_exp_f32_e32 v157, v157
	s_nop 0
	v_mul_f32_e32 v157, 0.15915494, v157
	v_lshl_add_u64 v[10:11], s[4:5], 0, v[176:177]
	v_lshlrev_b32_e32 v176, 1, v2
	v_lshlrev_b32_e32 v12, 1, v4
	v_lshlrev_b32_e32 v14, 1, v6
	s_branch .LBB0_992

.LBB0_994:
	v_and_b32_e32 v0, 2, v15
	v_cmp_eq_u32_e32 vcc, 0, v0
	global_load_dwordx4 v[4:7], v[16:17], off
	global_load_dwordx4 v[0:3], v[16:17], off offset:32
	v_cndmask_b32_e32 v22, v25, v24, vcc
	s_mov_b64 s[12:13], 0x800
	v_cmp_lt_u32_e32 vcc, 31, v15
	v_mul_f32_e32 v19, v22, v150
	v_floor_f32_e32 v19, v19
	v_fma_f32 v19, v22, v150, -v19
	v_sin_f32_e32 v18, v19
	v_cos_f32_e32 v20, v19
	v_add_u32_e32 v13, 0x200, v13
	s_or_b64 s[10:11], vcc, s[10:11]
	v_mul_f32_e32 v21, v22, v151
	v_floor_f32_e32 v21, v21
	v_fma_f32 v21, v22, v151, -v21
	v_sin_f32_e32 v19, v21
	v_cos_f32_e32 v21, v21
	s_waitcnt vmcnt(0)
	v_lshlrev_b32_e32 v26, 16, v4
	v_lshlrev_b32_e32 v28, 16, v0
	v_and_b32_e32 v29, 0xffff0000, v0
	v_and_b32_e32 v27, 0xffff0000, v4
	v_pk_mul_f32 v[30:31], v[20:21], v[28:29]
	s_nop 0
	v_pk_fma_f32 v[30:31], v[18:19], v[26:27], v[30:31]
	v_pk_mul_f32 v[18:19], v[18:19], v[28:29]
	v_lshlrev_b32_e32 v28, 16, v1
	v_pk_fma_f32 v[18:19], v[20:21], v[26:27], v[18:19] neg_lo:[0,0,1] neg_hi:[0,0,1]
	v_and_b32_e32 v29, 0xffff0000, v1
	v_cvt_pk_bf16_f32 v4, v18, v19
	v_cvt_pk_bf16_f32 v0, v30, v31
	v_lshlrev_b32_e32 v26, 16, v5
	v_and_b32_e32 v27, 0xffff0000, v5
	v_mul_f32_e32 v19, v22, v152
	v_floor_f32_e32 v19, v19
	v_fma_f32 v19, v22, v152, -v19
	v_sin_f32_e32 v18, v19
	v_cos_f32_e32 v20, v19
	s_nop 0
	v_mul_f32_e32 v21, v22, v153
	v_floor_f32_e32 v21, v21
	v_fma_f32 v21, v22, v153, -v21
	v_sin_f32_e32 v19, v21
	v_cos_f32_e32 v21, v21
	s_nop 0
	v_pk_mul_f32 v[30:31], v[20:21], v[28:29]
	s_nop 0
	v_pk_fma_f32 v[30:31], v[18:19], v[26:27], v[30:31]
	v_pk_mul_f32 v[18:19], v[18:19], v[28:29]
	v_lshlrev_b32_e32 v28, 16, v2
	v_pk_fma_f32 v[18:19], v[20:21], v[26:27], v[18:19] neg_lo:[0,0,1] neg_hi:[0,0,1]
	v_and_b32_e32 v29, 0xffff0000, v2
	v_cvt_pk_bf16_f32 v5, v18, v19
	v_cvt_pk_bf16_f32 v1, v30, v31
	v_lshlrev_b32_e32 v26, 16, v6
	v_and_b32_e32 v27, 0xffff0000, v6
	v_mul_f32_e32 v19, v22, v154
	v_floor_f32_e32 v19, v19
	v_fma_f32 v19, v22, v154, -v19
	v_sin_f32_e32 v18, v19
	v_cos_f32_e32 v20, v19
	s_nop 0
	v_mul_f32_e32 v21, v22, v155
	v_floor_f32_e32 v21, v21
	v_fma_f32 v21, v22, v155, -v21
	v_sin_f32_e32 v19, v21
	v_cos_f32_e32 v21, v21
	s_nop 0
	v_pk_mul_f32 v[30:31], v[20:21], v[28:29]
	s_nop 0
	v_pk_fma_f32 v[30:31], v[18:19], v[26:27], v[30:31]
	v_pk_mul_f32 v[18:19], v[18:19], v[28:29]
	v_cvt_pk_bf16_f32 v2, v30, v31
	v_pk_fma_f32 v[18:19], v[20:21], v[26:27], v[18:19] neg_lo:[0,0,1] neg_hi:[0,0,1]
	v_lshlrev_b32_e32 v26, 16, v3
	v_cvt_pk_bf16_f32 v6, v18, v19
	v_and_b32_e32 v27, 0xffff0000, v3
	v_mul_f32_e32 v19, v22, v156
	v_floor_f32_e32 v19, v19
	v_fma_f32 v19, v22, v156, -v19
	v_sin_f32_e32 v18, v19
	v_cos_f32_e32 v20, v19
	v_and_b32_e32 v23, 0xffff0000, v7
	v_mul_f32_e32 v21, v22, v157
	v_floor_f32_e32 v21, v21
	v_fma_f32 v21, v22, v157, -v21
	v_sin_f32_e32 v19, v21
	v_cos_f32_e32 v21, v21
	v_lshlrev_b32_e32 v22, 16, v7
	v_pk_mul_f32 v[28:29], v[20:21], v[26:27]
	s_nop 0
	v_pk_fma_f32 v[28:29], v[18:19], v[22:23], v[28:29]
	v_pk_mul_f32 v[18:19], v[18:19], v[26:27]
	v_cvt_pk_bf16_f32 v3, v28, v29
	v_pk_fma_f32 v[18:19], v[20:21], v[22:23], v[18:19] neg_lo:[0,0,1] neg_hi:[0,0,1]
	s_nop 0
	v_cvt_pk_bf16_f32 v7, v18, v19
	global_store_dwordx4 v[16:17], v[4:7], off sc1
	global_store_dwordx4 v[16:17], v[0:3], off offset:32 sc1
	v_lshl_add_u64 v[16:17], v[16:17], 0, s[12:13]
	s_nop 0
	v_add_u32_e32 v0, 64, v15
	v_mov_b32_e32 v15, v0
	s_andn2_b64 exec, exec, s[10:11]
	s_cbranch_execnz .LBB0_994
	s_or_b64 exec, exec, s[10:11]
